# v18: v16 + MLA steady-state loop unrolled by two with swapped score registers (drops 8 v_mov_b64 per key tile)
# baseline (speedup 1.0000x reference)
.LBB0_1187:
	s_or_b64 exec, exec, s[36:37]
	s_add_i32 s34, s34, 1
	s_bitcmp1_b32 s34, 0
	s_cselect_b32 s36, 0x3400, 0
	v_add_u32_e32 v112, s36, v180
	ds_read_b128 v[132:135], v112
	ds_read_b128 v[136:139], v112 offset:32
	v_exp_f32_e32 v174, v48
	v_exp_f32_e32 v175, v49
	v_exp_f32_e32 v182, v50
	s_waitcnt lgkmcnt(0)
	v_mfma_f32_32x32x16_bf16 v[80:95], v[132:135], v[100:103], v[32:47]
	v_exp_f32_e32 v183, v51
	v_exp_f32_e32 v184, v52
	v_exp_f32_e32 v185, v53
	v_exp_f32_e32 v186, v54
	v_exp_f32_e32 v187, v55
	v_exp_f32_e32 v188, v56
	v_exp_f32_e32 v189, v57
	v_mfma_f32_32x32x16_bf16 v[80:95], v[136:139], v[104:107], v[80:95]
	ds_read_b128 v[132:135], v112 offset:64
	ds_read_b128 v[136:139], v112 offset:96
	v_exp_f32_e32 v190, v58
	v_exp_f32_e32 v191, v59
	v_exp_f32_e32 v192, v60
	v_exp_f32_e32 v193, v61
	v_exp_f32_e32 v194, v62
	v_exp_f32_e32 v195, v63
	s_waitcnt lgkmcnt(0)
	v_mfma_f32_32x32x16_bf16 v[80:95], v[132:135], v[108:111], v[80:95]
	ds_read_b128 v[132:135], v112 offset:128
	ds_read_b128 v[48:51], v112 offset:160
	s_and_b64 s[18:19], s[18:19], exec
	s_cselect_b32 s18, 0x2400, 0
	v_exp_f32_e32 v198, v64
	v_exp_f32_e32 v199, v65
	v_exp_f32_e32 v200, v70
	v_mfma_f32_32x32x16_bf16 v[80:95], v[136:139], v[116:119], v[80:95]
	v_exp_f32_e32 v201, v71
	v_exp_f32_e32 v202, v72
	v_exp_f32_e32 v203, v73
	v_exp_f32_e32 v76, v76
	v_cvt_pk_bf16_f32 v71, v200, v201
	v_exp_f32_e32 v78, v78
	v_exp_f32_e32 v79, v79
	s_waitcnt lgkmcnt(0)
	v_mfma_f32_32x32x16_bf16 v[80:95], v[132:135], v[120:123], v[80:95]
	ds_read_b128 v[132:135], v112 offset:6656
	ds_read_b128 v[146:149], v112 offset:6688
	v_exp_f32_e32 v77, v77
	v_cmp_eq_u32_e32 vcc, s34, v173
	v_lshl_add_u64 v[142:143], v[142:143], 0, s[24:25]
	v_lshl_add_u64 v[162:163], v[162:163], 0, s[24:25]
	s_or_b64 s[2:3], vcc, s[2:3]
	v_mfma_f32_32x32x16_bf16 v[80:95], v[48:51], v[96:99], v[80:95]
	s_waitcnt lgkmcnt(0)
	v_mfma_f32_32x32x16_bf16 v[48:63], v[132:135], v[100:103], v[32:47]
	global_load_dwordx4 v[132:135], v[164:165], off
	ds_read_b128 v[150:153], v112 offset:6720
	ds_read_b128 v[154:157], v112 offset:6752
	ds_read_b128 v[158:161], v112 offset:6784
	ds_read_b128 v[136:139], v112 offset:6816
	v_add_u32_e32 v112, s18, v179
	v_lshl_add_u64 v[164:165], v[164:165], 0, s[0:1]
	v_mfma_f32_32x32x16_bf16 v[48:63], v[146:149], v[104:107], v[48:63]
	v_exp_f32_e32 v146, v66
	v_exp_f32_e32 v147, v67
	v_exp_f32_e32 v148, v68
	v_exp_f32_e32 v149, v69
	ds_read_b64_tr_b16 v[64:65], v112 offset:26624
	ds_read_b64_tr_b16 v[66:67], v112 offset:27776
	v_cvt_pk_bf16_f32 v68, v198, v199
	v_cvt_pk_bf16_f32 v69, v146, v147
	s_waitcnt lgkmcnt(0)
	v_mfma_f32_32x32x16_bf16 v[48:63], v[150:153], v[108:111], v[48:63]
	v_exp_f32_e32 v150, v74
	v_exp_f32_e32 v151, v75
	ds_read_b64_tr_b16 v[74:75], v112 offset:27840
	ds_read_b64_tr_b16 v[72:73], v112 offset:26688
	v_cvt_pk_bf16_f32 v70, v148, v149
	v_pk_add_f32 v[146:147], v[182:183], v[146:147]
	v_pk_add_f32 v[198:199], v[174:175], v[198:199]
	v_pk_add_f32 v[148:149], v[184:185], v[148:149]
	v_mfma_f32_32x32x16_bf16 v[0:15], v[64:67], v[68:71], v[0:15]
	ds_read_b64_tr_b16 v[64:65], v112 offset:28928
	ds_read_b64_tr_b16 v[66:67], v112 offset:30080
	v_add_f32_e64 v152, v194, v78
	v_add_f32_e64 v153, v195, v79
	s_waitcnt lgkmcnt(0)
	v_mfma_f32_32x32x16_bf16 v[16:31], v[72:75], v[68:71], v[16:31]
	ds_read_b64_tr_b16 v[74:75], v112 offset:30144
	ds_read_b64_tr_b16 v[72:73], v112 offset:28992
	v_cvt_pk_bf16_f32 v68, v202, v203
	v_cvt_pk_bf16_f32 v69, v150, v151
	v_cvt_pk_bf16_f32 v70, v76, v77
	v_cvt_pk_bf16_f32 v71, v78, v79
	v_mfma_f32_32x32x16_bf16 v[48:63], v[154:157], v[116:119], v[48:63]
	v_add_f32_e64 v154, v192, v76
	v_add_f32_e64 v155, v193, v77
	v_add_f32_e64 v156, v190, v150
	v_add_f32_e64 v157, v191, v151
	v_mfma_f32_32x32x16_bf16 v[0:15], v[64:67], v[68:71], v[0:15]
	s_waitcnt lgkmcnt(0)
	v_mfma_f32_32x32x16_bf16 v[16:31], v[72:75], v[68:71], v[16:31]
	v_cvt_pk_bf16_f32 v68, v174, v175
	v_cvt_pk_bf16_f32 v69, v182, v183
	v_cvt_pk_bf16_f32 v70, v184, v185
	v_cvt_pk_bf16_f32 v71, v186, v187
	v_mfma_f32_32x32x16_bf16 v[48:63], v[158:161], v[120:123], v[48:63]
	v_add_f32_e64 v160, v186, v200
	v_add_f32_e64 v161, v187, v201
	v_pk_mov_b32 v[200:201], v[198:199], v[146:147] op_sel:[1,0]
	v_mov_b32_e32 v199, v147
	v_pk_add_f32 v[64:65], v[200:201], v[198:199]
	v_pk_mov_b32 v[78:79], v[148:149], v[160:161] op_sel:[1,0]
	v_pk_add_f32 v[76:77], v[64:65], v[64:65] op_sel_hi:[0,1]
	ds_read_b64_tr_b16 v[64:65], v112 offset:31232
	ds_read_b64_tr_b16 v[66:67], v112 offset:32384
	ds_read_b64_tr_b16 v[74:75], v112 offset:32448
	ds_read_b64_tr_b16 v[72:73], v112 offset:31296
	s_waitcnt lgkmcnt(0)
	v_mfma_f32_32x32x16_bf16 v[0:15], v[64:67], v[68:71], v[0:15]
	ds_read_b64_tr_b16 v[64:65], v112 offset:33536
	ds_read_b64_tr_b16 v[66:67], v112 offset:34688
	v_mov_b32_e32 v149, v161
	v_add_f32_e64 v78, v78, v148
	v_add_f32_e64 v79, v79, v149
	v_pk_add_f32 v[158:159], v[188:189], v[202:203]
	v_pk_add_f32 v[78:79], v[78:79], v[78:79] op_sel_hi:[0,1]
	v_add_f32_e32 v147, v158, v159
	v_add_f32_e32 v149, v156, v157
	v_mfma_f32_32x32x16_bf16 v[16:31], v[72:75], v[68:71], v[16:31]
	ds_read_b64_tr_b16 v[74:75], v112 offset:34752
	ds_read_b64_tr_b16 v[72:73], v112 offset:33600
	v_cvt_pk_bf16_f32 v68, v188, v189
	v_cvt_pk_bf16_f32 v69, v190, v191
	v_cvt_pk_bf16_f32 v70, v192, v193
	v_cvt_pk_bf16_f32 v71, v194, v195
	v_mov_b32_e32 v146, v154
	v_mov_b32_e32 v148, v155
	s_waitcnt lgkmcnt(0)
	v_mfma_f32_32x32x16_bf16 v[0:15], v[64:67], v[68:71], v[0:15]
	v_mov_b32_e32 v76, v152
	v_mov_b32_e32 v78, v153
	v_add_f32_e64 v146, v146, v148
	v_add_f32_e64 v147, v147, v149
	v_add_f32_e64 v64, v76, v78
	v_add_f32_e64 v65, v77, v79
	v_pk_add_f32 v[64:65], v[146:147], v[64:65]
	s_barrier
	v_mfma_f32_32x32x16_bf16 v[16:31], v[72:75], v[68:71], v[16:31]
	v_add_f32_e32 v64, v64, v65
	v_add_f32_e32 v114, v114, v64
	v_mfma_f32_32x32x16_bf16 v[48:63], v[136:139], v[96:99], v[48:63]
	s_andn2_b64 exec, exec, s[2:3]
	s_cbranch_execz .Lmla_exitA
	s_bitcmp1_b32 s34, 0
	s_cselect_b64 s[18:19], -1, 0
	s_and_b64 s[36:37], s[18:19], exec
	s_cselect_b32 s36, 0x3400, 0
	s_add_i32 s46, s36, 0
	v_add3_u32 v64, s46, v168, v170
	s_waitcnt vmcnt(0)
	ds_write_b128 v64, v[128:131]
	s_and_saveexec_b64 s[36:37], s[6:7]
	v_add3_u32 v64, s46, v171, v172
	ds_write_b128 v64, v[124:127]
	s_or_b64 exec, exec, s[36:37]
	s_andn2_b32 s36, 1, s34
	s_mulk_i32 s36, 0x2400
	v_add_u32_e32 v64, s36, v115
	ds_write_b128 v64, v[132:135] offset:26624
	global_load_dwordx4 v[128:131], v[162:163], off
	s_and_saveexec_b64 s[36:37], s[6:7]
	s_cbranch_execz .Lmla_bodyB
	global_load_dwordx4 v[124:127], v[142:143], off
	s_branch .Lmla_bodyB
.Lmla_bodyB:
	s_or_b64 exec, exec, s[36:37]
	s_add_i32 s34, s34, 1
	s_bitcmp1_b32 s34, 0
	s_cselect_b32 s36, 0x3400, 0
	v_add_u32_e32 v112, s36, v180
	ds_read_b128 v[132:135], v112
	ds_read_b128 v[136:139], v112 offset:32
	v_exp_f32_e32 v174, v48
	v_exp_f32_e32 v175, v49
	v_exp_f32_e32 v182, v50
	s_waitcnt lgkmcnt(0)
	v_mfma_f32_32x32x16_bf16 v[64:79], v[132:135], v[100:103], v[32:47]
	v_exp_f32_e32 v183, v51
	v_exp_f32_e32 v184, v52
	v_exp_f32_e32 v185, v53
	v_exp_f32_e32 v186, v54
	v_exp_f32_e32 v187, v55
	v_exp_f32_e32 v188, v56
	v_exp_f32_e32 v189, v57
	v_mfma_f32_32x32x16_bf16 v[64:79], v[136:139], v[104:107], v[64:79]
	ds_read_b128 v[132:135], v112 offset:64
	ds_read_b128 v[136:139], v112 offset:96
	v_exp_f32_e32 v190, v58
	v_exp_f32_e32 v191, v59
	v_exp_f32_e32 v192, v60
	v_exp_f32_e32 v193, v61
	v_exp_f32_e32 v194, v62
	v_exp_f32_e32 v195, v63
	s_waitcnt lgkmcnt(0)
	v_mfma_f32_32x32x16_bf16 v[64:79], v[132:135], v[108:111], v[64:79]
	ds_read_b128 v[132:135], v112 offset:128
	ds_read_b128 v[48:51], v112 offset:160
	s_and_b64 s[18:19], s[18:19], exec
	s_cselect_b32 s18, 0x2400, 0
	v_exp_f32_e32 v198, v80
	v_exp_f32_e32 v199, v81
	v_exp_f32_e32 v200, v86
	v_mfma_f32_32x32x16_bf16 v[64:79], v[136:139], v[116:119], v[64:79]
	v_exp_f32_e32 v201, v87
	v_exp_f32_e32 v202, v88
	v_exp_f32_e32 v203, v89
	v_exp_f32_e32 v92, v92
	v_cvt_pk_bf16_f32 v87, v200, v201
	v_exp_f32_e32 v94, v94
	v_exp_f32_e32 v95, v95
	s_waitcnt lgkmcnt(0)
	v_mfma_f32_32x32x16_bf16 v[64:79], v[132:135], v[120:123], v[64:79]
	ds_read_b128 v[132:135], v112 offset:6656
	ds_read_b128 v[146:149], v112 offset:6688
	v_exp_f32_e32 v93, v93
	v_cmp_eq_u32_e32 vcc, s34, v173
	v_lshl_add_u64 v[142:143], v[142:143], 0, s[24:25]
	v_lshl_add_u64 v[162:163], v[162:163], 0, s[24:25]
	s_or_b64 s[2:3], vcc, s[2:3]
	v_mfma_f32_32x32x16_bf16 v[64:79], v[48:51], v[96:99], v[64:79]
	s_waitcnt lgkmcnt(0)
	v_mfma_f32_32x32x16_bf16 v[48:63], v[132:135], v[100:103], v[32:47]
	global_load_dwordx4 v[132:135], v[164:165], off
	ds_read_b128 v[150:153], v112 offset:6720
	ds_read_b128 v[154:157], v112 offset:6752
	ds_read_b128 v[158:161], v112 offset:6784
	ds_read_b128 v[136:139], v112 offset:6816
	v_add_u32_e32 v112, s18, v179
	v_lshl_add_u64 v[164:165], v[164:165], 0, s[0:1]
	v_mfma_f32_32x32x16_bf16 v[48:63], v[146:149], v[104:107], v[48:63]
	v_exp_f32_e32 v146, v82
	v_exp_f32_e32 v147, v83
	v_exp_f32_e32 v148, v84
	v_exp_f32_e32 v149, v85
	ds_read_b64_tr_b16 v[80:81], v112 offset:26624
	ds_read_b64_tr_b16 v[82:83], v112 offset:27776
	v_cvt_pk_bf16_f32 v84, v198, v199
	v_cvt_pk_bf16_f32 v85, v146, v147
	s_waitcnt lgkmcnt(0)
	v_mfma_f32_32x32x16_bf16 v[48:63], v[150:153], v[108:111], v[48:63]
	v_exp_f32_e32 v150, v90
	v_exp_f32_e32 v151, v91
	ds_read_b64_tr_b16 v[90:91], v112 offset:27840
	ds_read_b64_tr_b16 v[88:89], v112 offset:26688
	v_cvt_pk_bf16_f32 v86, v148, v149
	v_pk_add_f32 v[146:147], v[182:183], v[146:147]
	v_pk_add_f32 v[198:199], v[174:175], v[198:199]
	v_pk_add_f32 v[148:149], v[184:185], v[148:149]
	v_mfma_f32_32x32x16_bf16 v[0:15], v[80:83], v[84:87], v[0:15]
	ds_read_b64_tr_b16 v[80:81], v112 offset:28928
	ds_read_b64_tr_b16 v[82:83], v112 offset:30080
	v_add_f32_e64 v152, v194, v94
	v_add_f32_e64 v153, v195, v95
	s_waitcnt lgkmcnt(0)
	v_mfma_f32_32x32x16_bf16 v[16:31], v[88:91], v[84:87], v[16:31]
	ds_read_b64_tr_b16 v[90:91], v112 offset:30144
	ds_read_b64_tr_b16 v[88:89], v112 offset:28992
	v_cvt_pk_bf16_f32 v84, v202, v203
	v_cvt_pk_bf16_f32 v85, v150, v151
	v_cvt_pk_bf16_f32 v86, v92, v93
	v_cvt_pk_bf16_f32 v87, v94, v95
	v_mfma_f32_32x32x16_bf16 v[48:63], v[154:157], v[116:119], v[48:63]
	v_add_f32_e64 v154, v192, v92
	v_add_f32_e64 v155, v193, v93
	v_add_f32_e64 v156, v190, v150
	v_add_f32_e64 v157, v191, v151
	v_mfma_f32_32x32x16_bf16 v[0:15], v[80:83], v[84:87], v[0:15]
	s_waitcnt lgkmcnt(0)
	v_mfma_f32_32x32x16_bf16 v[16:31], v[88:91], v[84:87], v[16:31]
	v_cvt_pk_bf16_f32 v84, v174, v175
	v_cvt_pk_bf16_f32 v85, v182, v183
	v_cvt_pk_bf16_f32 v86, v184, v185
	v_cvt_pk_bf16_f32 v87, v186, v187
	v_mfma_f32_32x32x16_bf16 v[48:63], v[158:161], v[120:123], v[48:63]
	v_add_f32_e64 v160, v186, v200
	v_add_f32_e64 v161, v187, v201
	v_pk_mov_b32 v[200:201], v[198:199], v[146:147] op_sel:[1,0]
	v_mov_b32_e32 v199, v147
	v_pk_add_f32 v[80:81], v[200:201], v[198:199]
	v_pk_mov_b32 v[94:95], v[148:149], v[160:161] op_sel:[1,0]
	v_pk_add_f32 v[92:93], v[80:81], v[80:81] op_sel_hi:[0,1]
	ds_read_b64_tr_b16 v[80:81], v112 offset:31232
	ds_read_b64_tr_b16 v[82:83], v112 offset:32384
	ds_read_b64_tr_b16 v[90:91], v112 offset:32448
	ds_read_b64_tr_b16 v[88:89], v112 offset:31296
	s_waitcnt lgkmcnt(0)
	v_mfma_f32_32x32x16_bf16 v[0:15], v[80:83], v[84:87], v[0:15]
	ds_read_b64_tr_b16 v[80:81], v112 offset:33536
	ds_read_b64_tr_b16 v[82:83], v112 offset:34688
	v_mov_b32_e32 v149, v161
	v_add_f32_e64 v94, v94, v148
	v_add_f32_e64 v95, v95, v149
	v_pk_add_f32 v[158:159], v[188:189], v[202:203]
	v_pk_add_f32 v[94:95], v[94:95], v[94:95] op_sel_hi:[0,1]
	v_add_f32_e32 v147, v158, v159
	v_add_f32_e32 v149, v156, v157
	v_mfma_f32_32x32x16_bf16 v[16:31], v[88:91], v[84:87], v[16:31]
	ds_read_b64_tr_b16 v[90:91], v112 offset:34752
	ds_read_b64_tr_b16 v[88:89], v112 offset:33600
	v_cvt_pk_bf16_f32 v84, v188, v189
	v_cvt_pk_bf16_f32 v85, v190, v191
	v_cvt_pk_bf16_f32 v86, v192, v193
	v_cvt_pk_bf16_f32 v87, v194, v195
	v_mov_b32_e32 v146, v154
	v_mov_b32_e32 v148, v155
	s_waitcnt lgkmcnt(0)
	v_mfma_f32_32x32x16_bf16 v[0:15], v[80:83], v[84:87], v[0:15]
	v_mov_b32_e32 v92, v152
	v_mov_b32_e32 v94, v153
	v_add_f32_e64 v146, v146, v148
	v_add_f32_e64 v147, v147, v149
	v_add_f32_e64 v80, v92, v94
	v_add_f32_e64 v81, v93, v95
	v_pk_add_f32 v[80:81], v[146:147], v[80:81]
	s_barrier
	v_mfma_f32_32x32x16_bf16 v[16:31], v[88:91], v[84:87], v[16:31]
	v_add_f32_e32 v80, v80, v81
	v_add_f32_e32 v114, v114, v80
	v_mfma_f32_32x32x16_bf16 v[48:63], v[136:139], v[96:99], v[48:63]
	s_andn2_b64 exec, exec, s[2:3]
	s_cbranch_execz .LBB0_1192

.Lmla_exitA:
	s_or_b64 exec, exec, s[2:3]
	v_mov_b64_e32 v[64:65], v[80:81]
	v_mov_b64_e32 v[66:67], v[82:83]
	v_mov_b64_e32 v[68:69], v[84:85]
	v_mov_b64_e32 v[70:71], v[86:87]
	v_mov_b64_e32 v[72:73], v[88:89]
	v_mov_b64_e32 v[74:75], v[90:91]
	v_mov_b64_e32 v[76:77], v[92:93]
	v_mov_b64_e32 v[78:79], v[94:95]
